# P0 row-loop invariant loads hoisted; DN scan prologue spurious vmcnt(0) removed
# speedup vs baseline: 1.0054x; 1.0008x over previous
; #define GAS __attribute__((address_space(1)))
; #define LAS __attribute__((address_space(3)))
; __global__ void __launch_bounds__(NWAVES * 64, 2) fwd(Args args) {
;     ...
;         f32x4 wreg[8][4];
; #pragma unroll
;         for (int c = 0; c < 8; ++c)
; #pragma unroll
;             for (int j = 0; j < 4; ++j) wreg[c][j] = *(const LAS f32x4*)(w8 + c * 1024 + 256 * j + 4 * lane);
;         f32x4 vn[4];
;         if (gw < M) { const GAS f32x4* xr0 = (const GAS f32x4*)(x + (size_t)gw * D) + 2 * lane;
; #pragma unroll
;             for (int j = 0; j < 4; ++j) vn[j] = xr0[128 * (j >> 1) + (j & 1)]; }
;     ...
;             if ((lane & 7) == 0) { const int cc = lane >> 3; float r;
;                 if (cc < 4) r = 1.f / (1.f + expf(-a1));
;                 else { const int h = cc - 4; const float z = a1 + dt_bias[h]; const float sp = z > 20.f ? z : log1pf(expf(z)); r = -expf(A_log[h]) * sp; }
.LBB0_50:
	s_or_b64 exec, exec, s[6:7]
	s_cmpk_lt_i32 s40, 0x4000
	s_waitcnt lgkmcnt(0)
	s_barrier
	s_cbranch_scc0 .LBB0_65
	s_ashr_i32 s41, s40, 31
	s_lshl_b64 s[6:7], s[40:41], 12
	s_add_u32 s8, s16, s6
	s_addc_u32 s9, s17, s7
	v_lshlrev_b32_e32 v38, 5, v234
	global_load_dwordx4 v[146:149], v38, s[8:9]
	global_load_dwordx4 v[154:157], v38, s[8:9] offset:16
	global_load_dwordx4 v[150:153], v38, s[8:9] offset:2048
	global_load_dwordx4 v[158:161], v38, s[8:9] offset:2064
	v_mov_b32_e32 v39, 0
	v_lshl_add_u64 v[162:163], s[16:17], 0, v[38:39]
	s_lshl_b64 s[16:17], s[40:41], 5
	s_add_u32 s16, s60, s16
	v_mov_b32_e32 v35, v39
	s_addc_u32 s17, s61, s17
	v_lshl_add_u64 v[34:35], s[16:17], 0, v[34:35]
	s_mov_b64 s[16:17], 0x100000
	s_ashr_i32 s43, s42, 31
	v_and_b32_e32 v1, 32, v0
	v_lshl_add_u64 v[168:169], v[34:35], 0, s[16:17]
	s_lshl_b64 s[16:17], s[42:43], 5
	s_lshl_b64 s[20:21], s[40:41], 11
	v_cmp_eq_u32_e64 s[6:7], 0, v1
	v_and_b32_e32 v1, 16, v0
	s_add_u32 s20, s60, s20
	v_lshlrev_b32_e32 v36, 4, v234
	v_cmp_eq_u32_e64 s[8:9], 0, v1
	v_and_b32_e32 v1, 8, v0
	v_mov_b32_e32 v37, v39
	s_addc_u32 s21, s61, s21
	v_cmp_eq_u32_e64 s[10:11], 0, v1
	v_add_u32_e32 v2, -4, v8
	v_mov_b32_e32 v3, v39
	v_add_u32_e32 v1, 0, v36
	v_lshl_add_u64 v[34:35], s[20:21], 0, v[36:37]
	s_mov_b64 s[20:21], 0x4000400
	v_lshlrev_b64 v[2:3], 2, v[2:3]
	v_add_u32_e32 v126, 0x12000, v1
	v_lshl_add_u64 v[170:171], v[34:35], 0, s[20:21]
	v_cmp_eq_u32_e64 s[12:13], 0, v4
	v_lshl_add_u64 v[164:165], s[28:29], 0, v[2:3]
	v_lshl_add_u64 v[166:167], s[26:27], 0, v[2:3]
	ds_read_b128 v[2:5], v126 offset:31744
	ds_read_b128 v[6:9], v126 offset:30720
	ds_read_b128 v[10:13], v126 offset:29696
	ds_read_b128 v[14:17], v126 offset:28672
	ds_read_b128 v[18:21], v126 offset:27648
	ds_read_b128 v[22:25], v126 offset:26624
	ds_read_b128 v[26:29], v126 offset:25600
	ds_read_b128 v[30:33], v126 offset:24576
	ds_read_b128 v[34:37], v126 offset:23552
	ds_read_b128 v[38:41], v126 offset:22528
	ds_read_b128 v[42:45], v126 offset:21504
	ds_read_b128 v[46:49], v126 offset:20480
	ds_read_b128 v[50:53], v126 offset:19456
	ds_read_b128 v[54:57], v126 offset:18432
	ds_read_b128 v[58:61], v126 offset:17408
	ds_read_b128 v[62:65], v126 offset:16384
	ds_read_b128 v[66:69], v126 offset:15360
	ds_read_b128 v[70:73], v126 offset:14336
	ds_read_b128 v[74:77], v126 offset:13312
	ds_read_b128 v[78:81], v126 offset:12288
	ds_read_b128 v[82:85], v126 offset:11264
	ds_read_b128 v[86:89], v126 offset:10240
	ds_read_b128 v[90:93], v126 offset:9216
	ds_read_b128 v[94:97], v126 offset:8192
	ds_read_b128 v[98:101], v126 offset:7168
	ds_read_b128 v[102:105], v126 offset:6144
	ds_read_b128 v[106:109], v126 offset:5120
	ds_read_b128 v[110:113], v126 offset:4096
	ds_read_b128 v[114:117], v126 offset:3072
	ds_read_b128 v[118:121], v126 offset:2048
	ds_read_b128 v[122:125], v126 offset:1024
	ds_read_b128 v[126:129], v126
	v_mbcnt_lo_u32_b32 v1, -1, 0
	v_cmp_lt_u32_e64 s[14:15], 31, v234
	s_lshl_b64 s[20:21], s[42:43], 11
	v_mbcnt_hi_u32_b32 v1, -1, v1
	s_mov_b32 s3, 0x41a00000
	s_mov_b32 s4, 0x3fb8aa3b
	s_mov_b32 s33, 0xc2ce8ed0
	s_mov_b32 s35, 0x42b17218
	s_mov_b32 s36, 0x7f800000
	s_mov_b32 s37, 0x3f2aaaab
	v_mov_b32_e32 v174, 0x3ecc95a3
	s_mov_b32 s43, 0x3f317218
	s_mov_b32 s48, 0x33800000
	s_mov_b32 s49, 0xbfb8aa3b
	s_mov_b32 s50, 0x42ce8ed0
	s_mov_b32 s51, 0xc2b17218
	v_mov_b32_e32 v175, 0x7f800000
	v_mov_b32_e32 v172, 0x3f317218
	s_mov_b64 s[44:45], exec
	s_and_b64 exec, exec, s[14:15]
	global_load_dword v241, v[164:165], off
	global_load_dword v242, v[166:167], off
	s_mov_b64 exec, s[44:45]
	s_branch .LBB0_54

; __global__ void __launch_bounds__(NWAVES * 64, 2) fwd(Args args) {
;     ...
;             float acc[8];
; #pragma unroll
;             for (int c = 0; c < 8; ++c) { float a = 0.f;
; #pragma unroll
;                 for (int j = 0; j < 4; ++j) { const f32x4 w = wreg[c][j]; a += v[j].x * w.x + v[j].y * w.y + v[j].z * w.z + v[j].w * w.w; }
;                 acc[c] = a; }
;             float a4[4], a2[2], a1;
;             { const bool hi = (lane & 32) != 0;
; #pragma unroll
;               for (int i = 0; i < 4; ++i) { const float send = hi ? acc[i] : acc[4 + i], keep = hi ? acc[4 + i] : acc[i]; a4[i] = keep + __shfl_xor(send, 32); } }
.LBB0_57:
	s_waitcnt vmcnt(7) lgkmcnt(0)
	v_mul_f32_e32 v173, v147, v127
	v_fmac_f32_e32 v173, v146, v126
	s_waitcnt vmcnt(6)
	v_mul_f32_e32 v176, v155, v123
	v_fmac_f32_e32 v173, v148, v128
	v_fmac_f32_e32 v176, v154, v122
	v_fmac_f32_e32 v173, v149, v129
	v_fmac_f32_e32 v176, v156, v124
	v_add_f32_e32 v173, 0, v173
	v_fmac_f32_e32 v176, v157, v125
	v_add_f32_e32 v173, v173, v176
	s_waitcnt vmcnt(5)
	v_mul_f32_e32 v176, v151, v119
	v_fmac_f32_e32 v176, v150, v118
	v_fmac_f32_e32 v176, v152, v120
	v_fmac_f32_e32 v176, v153, v121
	v_add_f32_e32 v173, v173, v176
	s_waitcnt vmcnt(4)
	v_mul_f32_e32 v176, v159, v115
	v_fmac_f32_e32 v176, v158, v114
	v_fmac_f32_e32 v176, v160, v116
	v_fmac_f32_e32 v176, v161, v117
	v_add_f32_e32 v173, v173, v176
	v_mul_f32_e32 v176, v147, v111
	v_fmac_f32_e32 v176, v146, v110
	v_mul_f32_e32 v177, v155, v107
	v_fmac_f32_e32 v176, v148, v112
	v_fmac_f32_e32 v177, v154, v106
	v_fmac_f32_e32 v176, v149, v113
	v_fmac_f32_e32 v177, v156, v108
	v_add_f32_e32 v176, 0, v176
	v_fmac_f32_e32 v177, v157, v109
	v_add_f32_e32 v176, v176, v177
	v_mul_f32_e32 v177, v151, v103
	v_fmac_f32_e32 v177, v150, v102
	v_fmac_f32_e32 v177, v152, v104
	v_fmac_f32_e32 v177, v153, v105
	v_add_f32_e32 v176, v176, v177
	v_mul_f32_e32 v177, v159, v99
	v_fmac_f32_e32 v177, v158, v98
	v_fmac_f32_e32 v177, v160, v100
	v_fmac_f32_e32 v177, v161, v101
	v_add_f32_e32 v176, v176, v177
	v_mul_f32_e32 v177, v147, v95
	v_fmac_f32_e32 v177, v146, v94
	v_mul_f32_e32 v178, v155, v91
	v_fmac_f32_e32 v177, v148, v96
	v_fmac_f32_e32 v178, v154, v90
	v_fmac_f32_e32 v177, v149, v97
	v_fmac_f32_e32 v178, v156, v92
	v_add_f32_e32 v177, 0, v177
	v_fmac_f32_e32 v178, v157, v93
	v_add_f32_e32 v177, v177, v178
	v_mul_f32_e32 v178, v151, v87
	v_fmac_f32_e32 v178, v150, v86
	v_fmac_f32_e32 v178, v152, v88
	v_fmac_f32_e32 v178, v153, v89
	v_add_f32_e32 v177, v177, v178
	v_mul_f32_e32 v178, v159, v83
	v_fmac_f32_e32 v178, v158, v82
	v_fmac_f32_e32 v178, v160, v84
	v_fmac_f32_e32 v178, v161, v85
	v_add_f32_e32 v177, v177, v178
	v_mul_f32_e32 v178, v147, v79
	v_fmac_f32_e32 v178, v146, v78
	v_mul_f32_e32 v179, v155, v75
	v_fmac_f32_e32 v178, v148, v80
	v_fmac_f32_e32 v179, v154, v74
	v_fmac_f32_e32 v178, v149, v81
	v_fmac_f32_e32 v179, v156, v76
	v_add_f32_e32 v178, 0, v178
	v_fmac_f32_e32 v179, v157, v77
	v_add_f32_e32 v178, v178, v179
	v_mul_f32_e32 v179, v151, v71
	v_fmac_f32_e32 v179, v150, v70
	v_fmac_f32_e32 v179, v152, v72
	v_fmac_f32_e32 v179, v153, v73
	v_add_f32_e32 v178, v178, v179
	v_mul_f32_e32 v179, v159, v67
	v_fmac_f32_e32 v179, v158, v66
	v_fmac_f32_e32 v179, v160, v68
	v_fmac_f32_e32 v179, v161, v69
	v_add_f32_e32 v178, v178, v179
	v_mul_f32_e32 v179, v147, v63
	v_fmac_f32_e32 v179, v146, v62
	v_mul_f32_e32 v180, v155, v59
	v_fmac_f32_e32 v179, v148, v64
	v_fmac_f32_e32 v180, v154, v58
	v_fmac_f32_e32 v179, v149, v65
	v_fmac_f32_e32 v180, v156, v60
	v_add_f32_e32 v179, 0, v179
	v_fmac_f32_e32 v180, v157, v61
	v_add_f32_e32 v179, v179, v180
	v_mul_f32_e32 v180, v151, v55
	v_fmac_f32_e32 v180, v150, v54
	v_fmac_f32_e32 v180, v152, v56
	v_fmac_f32_e32 v180, v153, v57
	v_add_f32_e32 v179, v179, v180
	v_mul_f32_e32 v180, v159, v51
	v_fmac_f32_e32 v180, v158, v50
	v_fmac_f32_e32 v180, v160, v52
	v_fmac_f32_e32 v180, v161, v53
	v_add_f32_e32 v179, v179, v180
	v_mul_f32_e32 v180, v147, v47
	v_fmac_f32_e32 v180, v146, v46
	v_mul_f32_e32 v181, v155, v43
	v_fmac_f32_e32 v180, v148, v48
	v_fmac_f32_e32 v181, v154, v42
	v_fmac_f32_e32 v180, v149, v49
	v_fmac_f32_e32 v181, v156, v44
	v_add_f32_e32 v180, 0, v180
	v_fmac_f32_e32 v181, v157, v45
	v_add_f32_e32 v180, v180, v181
	v_mul_f32_e32 v181, v151, v39
	v_fmac_f32_e32 v181, v150, v38
	v_fmac_f32_e32 v181, v152, v40
	v_fmac_f32_e32 v181, v153, v41
	v_add_f32_e32 v180, v180, v181
	v_mul_f32_e32 v181, v159, v35
	v_fmac_f32_e32 v181, v158, v34
	v_fmac_f32_e32 v181, v160, v36
	v_fmac_f32_e32 v181, v161, v37
	v_add_f32_e32 v180, v180, v181
	v_mul_f32_e32 v181, v147, v31
	v_fmac_f32_e32 v181, v146, v30
	v_mul_f32_e32 v182, v155, v27
	v_fmac_f32_e32 v181, v148, v32
	v_fmac_f32_e32 v182, v154, v26
	v_fmac_f32_e32 v181, v149, v33
	v_fmac_f32_e32 v182, v156, v28
	v_add_f32_e32 v181, 0, v181
	v_fmac_f32_e32 v182, v157, v29
	v_add_f32_e32 v181, v181, v182
	v_mul_f32_e32 v182, v151, v23
	v_fmac_f32_e32 v182, v150, v22
	v_fmac_f32_e32 v182, v152, v24
	v_fmac_f32_e32 v182, v153, v25
	v_add_f32_e32 v181, v181, v182
	v_mul_f32_e32 v182, v159, v19
	v_fmac_f32_e32 v182, v158, v18
	v_fmac_f32_e32 v182, v160, v20
	v_fmac_f32_e32 v182, v161, v21
	v_add_f32_e32 v181, v181, v182
	v_mul_f32_e32 v182, v147, v15
	v_fmac_f32_e32 v182, v146, v14
	v_mul_f32_e32 v183, v155, v11
	v_fmac_f32_e32 v182, v148, v16
	v_fmac_f32_e32 v183, v154, v10
	v_fmac_f32_e32 v182, v149, v17
	v_fmac_f32_e32 v183, v156, v12
	v_add_f32_e32 v182, 0, v182
	v_fmac_f32_e32 v183, v157, v13
	v_add_f32_e32 v182, v182, v183
	v_mul_f32_e32 v183, v151, v7
	v_fmac_f32_e32 v183, v150, v6
	v_fmac_f32_e32 v183, v152, v8
	v_fmac_f32_e32 v183, v153, v9
	v_and_b32_e32 v186, 64, v1
	v_add_f32_e32 v182, v182, v183
	v_mul_f32_e32 v183, v159, v3
	v_xor_b32_e32 v185, 32, v1
	v_add_u32_e32 v186, 64, v186
	v_fmac_f32_e32 v183, v158, v2
	v_cmp_lt_i32_e32 vcc, v185, v186
	v_fmac_f32_e32 v183, v160, v4
	v_cndmask_b32_e64 v187, v173, v179, s[6:7]
	v_cndmask_b32_e32 v185, v1, v185, vcc
	v_lshlrev_b32_e32 v185, 2, v185
	v_fmac_f32_e32 v183, v161, v5
	v_cndmask_b32_e64 v173, v179, v173, s[6:7]
	v_cndmask_b32_e64 v179, v176, v180, s[6:7]
	v_add_f32_e32 v182, v182, v183
	ds_bpermute_b32 v179, v185, v179
	v_cndmask_b32_e64 v176, v180, v176, s[6:7]
	v_cndmask_b32_e64 v180, v177, v181, s[6:7]
	v_cndmask_b32_e64 v183, v178, v182, s[6:7]
	ds_bpermute_b32 v187, v185, v187
	ds_bpermute_b32 v180, v185, v180
	ds_bpermute_b32 v183, v185, v183
	s_waitcnt lgkmcnt(3)
; #define GAS __attribute__((address_space(1)))
; __device__ __forceinline__ unsigned pk2(float lo, float hi) { const f32x2_t v = {lo, hi}; return __builtin_bit_cast(unsigned, __builtin_convertvector(v, bf16x2_t)); }
; __global__ void __launch_bounds__(NWAVES * 64, 2) fwd(Args args) {
;     ...
;             GAS v4u* o16 = (GAS v4u*)(XB + (size_t)m * D) + lane;
; #pragma unroll
;             for (int jj = 0; jj < 2; ++jj) { v4u o; o.x = pk2(v[2 * jj].x, v[2 * jj].y); o.y = pk2(v[2 * jj].z, v[2 * jj].w); o.z = pk2(v[2 * jj + 1].x, v[2 * jj + 1].y); o.w = pk2(v[2 * jj + 1].z, v[2 * jj + 1].w); o16[64 * jj] = o; }
;     ...
;             { const bool hi = (lane & 32) != 0;
; #pragma unroll
;               for (int i = 0; i < 4; ++i) { const float send = hi ? acc[i] : acc[4 + i], keep = hi ? acc[4 + i] : acc[i]; a4[i] = keep + __shfl_xor(send, 32); } }
;             { const bool hi = (lane & 16) != 0;
; #pragma unroll
;               for (int i = 0; i < 2; ++i) { const float send = hi ? a4[i] : a4[2 + i], keep = hi ? a4[2 + i] : a4[i]; a2[i] = keep + __shfl_xor(send, 16); } }
;             { const bool hi = (lane & 8) != 0; const float send = hi ? a2[0] : a2[1], keep = hi ? a2[1] : a2[0]; a1 = keep + __shfl_xor(send, 8); }
;             a1 += __shfl_xor(a1, 4); a1 += __shfl_xor(a1, 2); a1 += __shfl_xor(a1, 1);
;             if ((lane & 7) == 0) { const int cc = lane >> 3; float r;
;                 if (cc < 4) r = 1.f / (1.f + expf(-a1));
;                 else { const int h = cc - 4; const float z = a1 + dt_bias[h]; const float sp = z > 20.f ? z : log1pf(expf(z)); r = -expf(A_log[h]) * sp; }
	v_add_f32_e32 v176, v176, v179
	v_xor_b32_e32 v179, 16, v1
	v_cndmask_b32_e64 v177, v181, v177, s[6:7]
	v_cndmask_b32_e64 v178, v182, v178, s[6:7]
	v_cmp_lt_i32_e32 vcc, v179, v186
	s_waitcnt lgkmcnt(2)
	v_add_f32_e32 v173, v173, v187
	s_waitcnt lgkmcnt(1)
	v_add_f32_e32 v177, v177, v180
	s_waitcnt lgkmcnt(0)
	v_add_f32_e32 v178, v178, v183
	v_cndmask_b32_e32 v179, v1, v179, vcc
	v_lshlrev_b32_e32 v179, 2, v179
	v_cndmask_b32_e64 v180, v173, v177, s[8:9]
	v_cndmask_b32_e64 v181, v176, v178, s[8:9]
	ds_bpermute_b32 v180, v179, v180
	ds_bpermute_b32 v179, v179, v181
	v_cndmask_b32_e64 v176, v178, v176, s[8:9]
	v_xor_b32_e32 v178, 8, v1
	v_cndmask_b32_e64 v173, v177, v173, s[8:9]
	v_cmp_lt_i32_e32 vcc, v178, v186
	s_waitcnt lgkmcnt(1)
	v_add_f32_e32 v173, v173, v180
	s_waitcnt lgkmcnt(0)
	v_add_f32_e32 v176, v176, v179
	v_cndmask_b32_e32 v178, v1, v178, vcc
	v_cndmask_b32_e64 v177, v173, v176, s[10:11]
	v_lshlrev_b32_e32 v178, 2, v178
	ds_bpermute_b32 v177, v178, v177
	v_cndmask_b32_e64 v173, v176, v173, s[10:11]
	v_xor_b32_e32 v176, 4, v1
	v_cmp_lt_i32_e32 vcc, v176, v186
	s_waitcnt lgkmcnt(0)
	v_add_f32_e32 v173, v173, v177
	v_cvt_pk_bf16_f32 v146, v146, v147
	v_cndmask_b32_e32 v176, v1, v176, vcc
	v_lshlrev_b32_e32 v176, 2, v176
	ds_bpermute_b32 v176, v176, v173
	v_cvt_pk_bf16_f32 v147, v148, v149
	v_xor_b32_e32 v148, 2, v1
	v_cmp_lt_i32_e32 vcc, v148, v186
	v_cvt_pk_bf16_f32 v149, v156, v157
	s_waitcnt lgkmcnt(0)
	v_add_f32_e32 v173, v173, v176
	v_cndmask_b32_e32 v148, v1, v148, vcc
	v_lshlrev_b32_e32 v148, 2, v148
	ds_bpermute_b32 v176, v148, v173
	v_cvt_pk_bf16_f32 v148, v154, v155
	global_store_dwordx4 v[170:171], v[146:149], off offset:-1024
	s_nop 1
	v_xor_b32_e32 v147, 1, v1
	v_cmp_lt_i32_e32 vcc, v147, v186
	s_waitcnt lgkmcnt(0)
	v_add_f32_e32 v146, v173, v176
	v_cvt_pk_bf16_f32 v148, v150, v151
	v_cndmask_b32_e32 v147, v1, v147, vcc
	v_lshlrev_b32_e32 v147, 2, v147
	ds_bpermute_b32 v147, v147, v146
	v_cvt_pk_bf16_f32 v149, v152, v153
	v_cvt_pk_bf16_f32 v150, v158, v159
	v_cvt_pk_bf16_f32 v151, v160, v161
	global_store_dwordx4 v[170:171], v[148:151], off
	s_and_saveexec_b64 s[28:29], s[12:13]
	s_cbranch_execz .LBB0_53
	s_waitcnt lgkmcnt(0)
	v_add_f32_e32 v146, v146, v147
	s_and_saveexec_b64 s[44:45], s[14:15]
	s_xor_b64 s[44:45], exec, s[44:45]
	s_cbranch_execz .LBB0_62
	v_add_f32_e32 v146, v146, v241
	v_cmp_nlt_f32_e32 vcc, s3, v146
	s_and_saveexec_b64 s[46:47], vcc
	s_cbranch_execz .LBB0_61
; __global__ void __launch_bounds__(NWAVES * 64, 2) fwd(Args args) {
;     ...
;             if ((lane & 7) == 0) { const int cc = lane >> 3; float r;
;                 if (cc < 4) r = 1.f / (1.f + expf(-a1));
;                 else { const int h = cc - 4; const float z = a1 + dt_bias[h]; const float sp = z > 20.f ? z : log1pf(expf(z)); r = -expf(A_log[h]) * sp; }
;                 GBT[(size_t)m * 8 + cc] = r;
	v_mul_f32_e32 v147, 0x3fb8aa3b, v146
	v_rndne_f32_e32 v148, v147
	v_sub_f32_e32 v149, v147, v148
	v_fma_f32 v147, v146, s4, -v147
	v_fmac_f32_e32 v147, 0x32a5705f, v146
	v_add_f32_e32 v147, v149, v147
	v_cvt_i32_f32_e32 v148, v148
	v_exp_f32_e32 v147, v147
	v_cmp_ngt_f32_e32 vcc, s33, v146
	v_ldexp_f32 v147, v147, v148
	s_nop 0
	v_cndmask_b32_e32 v147, 0, v147, vcc
	v_cmp_nlt_f32_e32 vcc, s35, v146
	s_nop 1
	v_cndmask_b32_e32 v160, v175, v147, vcc
	v_add_f32_e32 v148, 1.0, v160
	v_add_f32_e32 v146, -1.0, v148
	v_sub_f32_e32 v147, v146, v148
	v_add_f32_e32 v147, 1.0, v147
	v_sub_f32_e32 v146, v160, v146
	v_add_f32_e32 v149, v146, v147
	v_frexp_mant_f32_e32 v150, v148
	v_cvt_f64_f32_e32 v[146:147], v148
	v_frexp_exp_i32_f64_e32 v146, v[146:147]
	v_cmp_gt_f32_e32 vcc, s37, v150
	s_nop 1
	v_subbrev_co_u32_e32 v154, vcc, 0, v146, vcc
	v_sub_u32_e32 v146, 0, v154
	v_ldexp_f32 v147, v148, v146
	v_add_f32_e32 v148, -1.0, v147
	v_add_f32_e32 v150, 1.0, v147
	v_ldexp_f32 v146, v149, v146
	v_add_f32_e32 v149, 1.0, v148
	v_add_f32_e32 v151, -1.0, v150
	v_sub_f32_e32 v149, v147, v149
	v_sub_f32_e32 v147, v147, v151
	v_add_f32_e32 v149, v146, v149
	v_add_f32_e32 v146, v146, v147
	v_add_f32_e32 v155, v150, v146
	v_rcp_f32_e32 v157, v155
	v_sub_f32_e32 v147, v150, v155
	v_add_f32_e32 v156, v146, v147
	v_add_f32_e32 v147, v148, v149
	v_mul_f32_e32 v159, v147, v157
	v_sub_f32_e32 v146, v148, v147
	v_mul_f32_e32 v148, v155, v159
	v_fma_f32 v150, v159, v155, -v148
	v_fmac_f32_e32 v150, v159, v156
	v_add_f32_e32 v158, v149, v146
	v_add_f32_e32 v146, v148, v150
	v_sub_f32_e32 v149, v147, v146
	v_pk_add_f32 v[152:153], v[146:147], v[148:149] neg_lo:[0,1] neg_hi:[0,1]
	v_mov_b32_e32 v151, v146
	v_pk_add_f32 v[146:147], v[152:153], v[150:151] neg_lo:[0,1] neg_hi:[0,1]
	v_cmp_neq_f32_e32 vcc, s36, v160
	v_add_f32_e32 v147, v158, v147
	v_add_f32_e32 v146, v146, v147
	v_add_f32_e32 v147, v149, v146
	v_mul_f32_e32 v158, v157, v147
	v_mul_f32_e32 v148, v155, v158
	v_fma_f32 v150, v158, v155, -v148
	v_fmac_f32_e32 v150, v158, v156
	v_sub_f32_e32 v149, v149, v147
	v_add_f32_e32 v155, v146, v149
	v_add_f32_e32 v146, v148, v150
	v_sub_f32_e32 v149, v147, v146
	v_pk_add_f32 v[152:153], v[146:147], v[148:149] neg_lo:[0,1] neg_hi:[0,1]
	v_mov_b32_e32 v151, v146
	v_pk_add_f32 v[146:147], v[152:153], v[150:151] neg_lo:[0,1] neg_hi:[0,1]
	s_nop 0
	v_add_f32_e32 v147, v155, v147
	v_add_f32_e32 v146, v146, v147
	v_add_f32_e32 v147, v159, v158
	v_add_f32_e32 v146, v149, v146
	v_sub_f32_e32 v148, v147, v159
	v_mul_f32_e32 v146, v157, v146
	v_sub_f32_e32 v148, v158, v148
	v_add_f32_e32 v148, v148, v146
	v_add_f32_e32 v150, v147, v148
	v_mul_f32_e32 v151, v150, v150
	v_fmamk_f32 v146, v151, 0x3e9b6dac, v174
	v_fmaak_f32 v173, v151, v146, 0x3f2aaada
	v_cvt_f32_i32_e32 v146, v154
	v_sub_f32_e32 v147, v150, v147
	v_sub_f32_e32 v147, v148, v147
	v_ldexp_f32 v152, v147, 1
	v_mul_f32_e32 v147, v150, v151
	v_ldexp_f32 v149, v150, 1
	v_pk_mul_f32 v[150:151], v[146:147], v[172:173]
	s_nop 0
	v_fma_f32 v148, v146, s43, -v150
	v_fmac_f32_e32 v148, 0xb102e308, v146
	v_pk_add_f32 v[146:147], v[150:151], v[148:149]
	s_nop 0
	v_sub_f32_e32 v149, v147, v149
	v_sub_f32_e32 v149, v151, v149
	v_add_f32_e32 v153, v152, v149
	v_mov_b32_e32 v152, v150
	v_pk_add_f32 v[150:151], v[146:147], v[150:151] neg_lo:[0,1] neg_hi:[0,1]
	v_pk_add_f32 v[154:155], v[146:147], v[152:153]
	v_mov_b32_e32 v149, v146
	v_mov_b32_e32 v151, v155
	v_pk_add_f32 v[156:157], v[148:149], v[150:151] neg_lo:[0,1] neg_hi:[0,1]
	v_pk_add_f32 v[148:149], v[148:149], v[150:151]
	v_mov_b32_e32 v152, v153
	v_pk_add_f32 v[150:151], v[148:149], v[146:147] op_sel:[1,0] op_sel_hi:[0,1] neg_lo:[0,1] neg_hi:[0,1]
	v_pk_add_f32 v[158:159], v[154:155], v[150:151] op_sel_hi:[1,0] neg_lo:[0,1] neg_hi:[0,1]
	v_mov_b32_e32 v154, v155
	v_mov_b32_e32 v155, v149
	v_pk_mov_b32 v[150:151], v[146:147], v[150:151] op_sel:[1,0]
	v_mov_b32_e32 v153, v146
	v_pk_add_f32 v[150:151], v[154:155], v[150:151] neg_lo:[0,1] neg_hi:[0,1]
	v_mov_b32_e32 v158, v156
	v_pk_add_f32 v[146:147], v[152:153], v[150:151] neg_lo:[0,1] neg_hi:[0,1]
	v_mov_b32_e32 v157, v149
	v_pk_add_f32 v[150:151], v[158:159], v[146:147]
	s_nop 0
	v_pk_add_f32 v[152:153], v[150:151], v[150:151] op_sel:[0,1] op_sel_hi:[1,0]
	s_nop 0
	v_pk_add_f32 v[148:149], v[148:149], v[152:153] op_sel:[1,0] op_sel_hi:[0,1]
	v_mov_b32_e32 v151, v148
	v_pk_add_f32 v[154:155], v[150:151], v[156:157] neg_lo:[0,1] neg_hi:[0,1]
	v_mov_b32_e32 v147, v152
	v_sub_f32_e32 v149, v150, v154
	v_pk_add_f32 v[146:147], v[146:147], v[154:155] neg_lo:[0,1] neg_hi:[0,1]
	v_sub_f32_e32 v149, v156, v149
	v_add_f32_e32 v146, v146, v149
	v_add_f32_e32 v146, v146, v147
	v_add_f32_e32 v146, v148, v146
	v_cndmask_b32_e32 v146, v175, v146, vcc
	v_cmp_lt_f32_e64 vcc, |v160|, s48
	s_nop 1
	v_cndmask_b32_e32 v146, v146, v160, vcc
.LBB0_61:
	s_or_b64 exec, exec, s[46:47]
	v_mov_b32_e32 v147, v242
	v_mul_f32_e32 v148, 0x3fb8aa3b, v147
	v_rndne_f32_e32 v149, v148
	v_fma_f32 v150, v147, s4, -v148
	v_sub_f32_e32 v148, v148, v149
	v_fmac_f32_e32 v150, 0x32a5705f, v147
	v_add_f32_e32 v148, v148, v150
	v_cvt_i32_f32_e32 v149, v149
	v_exp_f32_e32 v148, v148
	v_cmp_ngt_f32_e32 vcc, s33, v147
	v_ldexp_f32 v148, v148, v149
	s_nop 0
	v_cndmask_b32_e32 v148, 0, v148, vcc
	v_cmp_nlt_f32_e32 vcc, s35, v147
	s_nop 1
	v_cndmask_b32_e32 v147, v175, v148, vcc
	v_mul_f32_e64 v147, v146, -v147

;     const int b = job >> 4, h = (job >> 2) & 3, sl = job & 3;
;     f32x4 acc[2]; acc[0] = (f32x4){0.f, 0.f, 0.f, 0.f}; acc[1] = acc[0];
;     DnPre p0, p1, p2, p3, p4, p5;
;     DN_ISSUE(p0, 0); DN_ISSUE(p1, 1); DN_ISSUE(p2, 2); DN_ISSUE(p3, 3); DN_ISSUE(p4, 4); DN_ISSUE(p5, 5);
.LBB0_673:
	s_and_b64 vcc, exec, s[0:1]
	s_cbranch_vccz .LBB0_840
	s_lshl_b32 s0, s2, 2
	s_and_b32 s4, s0, 28
	s_add_u32 s33, s60, 0x200000
	s_addc_u32 s36, s61, 0
	s_lshl_b32 s0, s2, 5
	s_and_b32 s29, s0, 0x80
	s_and_b32 s5, s2, 3
	s_lshl_b32 s19, s29, 2
	s_or_b32 s28, s5, s19
	s_and_b32 s18, s2, 7
	s_lshl_b32 s0, s28, 16
	s_add_u32 s6, s62, s0
	s_addc_u32 s7, s63, 0
	s_lshl_b32 s0, s28, 15
	s_add_u32 s8, s64, s0
	s_addc_u32 s9, s65, 0
	s_lshl_b32 s0, s48, 5
	v_lshl_or_b32 v98, s48, 8, v234
	v_mov_b32_e32 v99, 0
	s_lshl_b32 s11, s73, 9
	s_and_b32 s3, s0, 0x7fffffc0
	v_lshlrev_b64 v[108:109], 4, v[98:99]
	s_add_i32 s0, s3, s11
	s_waitcnt vmcnt(6)
	v_lshl_add_u64 v[2:3], s[6:7], 0, v[108:109]
	s_mov_b64 s[6:7], 0x4000
	v_or_b32_e32 v4, s0, v234
	s_bfe_u32 s35, s66, 0x10006
	v_lshl_add_u64 v[2:3], v[2:3], 0, s[6:7]
	v_ashrrev_i32_e32 v5, 31, v4
	s_lshl_b32 s0, s35, 3
	s_lshl_b32 s10, s28, 9
	s_waitcnt vmcnt(4)
	global_load_dwordx4 v[18:21], v[2:3], off
	v_lshlrev_b64 v[106:107], 4, v[4:5]
	s_add_u32 s38, s33, s10
	global_load_dwordx4 v[22:25], v[2:3], off offset:1024
	s_mov_b32 s1, 0
	v_lshl_add_u64 v[4:5], s[8:9], 0, v[106:107]
	s_addc_u32 s39, s36, 0
	global_load_dwordx4 v[10:13], v[2:3], off offset:2048
	s_or_b32 s10, s28, 4
	v_lshl_add_u64 v[6:7], v[4:5], 0, s[0:1]
	s_mov_b64 s[8:9], 0x1000
	global_load_dwordx4 v[2:5], v[2:3], off offset:3072
	s_lshl_b32 s37, s10, 16
	v_lshl_add_u64 v[8:9], v[6:7], 0, s[8:9]
	global_load_dwordx2 v[124:125], v[6:7], off
	v_mov_b64_e32 v[6:7], s[38:39]
	s_add_u32 s38, s62, s37
	global_load_dwordx2 v[142:143], v[8:9], off
	s_addc_u32 s39, s63, 0
	s_lshl_b32 s37, s10, 15
	global_load_dword v113, v[6:7], off
	v_lshl_add_u64 v[6:7], s[38:39], 0, v[108:109]
	s_add_u32 s38, s64, s37
	v_lshl_add_u64 v[6:7], v[6:7], 0, s[6:7]
	s_addc_u32 s39, s65, 0
	s_lshl_b32 s10, s10, 9
	global_load_dwordx4 v[62:65], v[6:7], off
	v_lshl_add_u64 v[8:9], s[38:39], 0, v[106:107]
	s_add_u32 s38, s33, s10
	global_load_dwordx4 v[58:61], v[6:7], off offset:1024
	s_addc_u32 s39, s36, 0
	global_load_dwordx4 v[14:17], v[6:7], off offset:2048
	s_or_b32 s10, s28, 8
	v_lshl_add_u64 v[26:27], v[8:9], 0, s[0:1]
	global_load_dwordx4 v[6:9], v[6:7], off offset:3072
	s_lshl_b32 s37, s10, 16
	v_lshl_add_u64 v[28:29], v[26:27], 0, s[8:9]
	global_load_dwordx2 v[140:141], v[26:27], off
	v_mov_b64_e32 v[26:27], s[38:39]
	s_add_u32 s38, s62, s37
	global_load_dwordx2 v[136:137], v[28:29], off
	s_addc_u32 s39, s63, 0
	s_lshl_b32 s37, s10, 15
	global_load_dword v138, v[26:27], off
	v_lshl_add_u64 v[26:27], s[38:39], 0, v[108:109]
	s_add_u32 s38, s64, s37
	v_lshl_add_u64 v[26:27], v[26:27], 0, s[6:7]
	s_addc_u32 s39, s65, 0
	s_lshl_b32 s10, s10, 9
	global_load_dwordx4 v[38:41], v[26:27], off
	v_lshl_add_u64 v[28:29], s[38:39], 0, v[106:107]
	s_add_u32 s38, s33, s10
	global_load_dwordx4 v[34:37], v[26:27], off offset:1024
	s_addc_u32 s39, s36, 0
	global_load_dwordx4 v[30:33], v[26:27], off offset:2048
	s_or_b32 s10, s28, 12
	v_lshl_add_u64 v[42:43], v[28:29], 0, s[0:1]
	global_load_dwordx4 v[26:29], v[26:27], off offset:3072
	s_lshl_b32 s37, s10, 16
	v_lshl_add_u64 v[44:45], v[42:43], 0, s[8:9]
	global_load_dwordx2 v[130:131], v[42:43], off
	v_mov_b64_e32 v[42:43], s[38:39]
	s_add_u32 s38, s62, s37
	global_load_dwordx2 v[126:127], v[44:45], off
	s_addc_u32 s39, s63, 0
	s_lshl_b32 s37, s10, 15
	global_load_dword v128, v[42:43], off
	v_lshl_add_u64 v[42:43], s[38:39], 0, v[108:109]
	s_add_u32 s38, s64, s37
	v_lshl_add_u64 v[42:43], v[42:43], 0, s[6:7]
	s_addc_u32 s39, s65, 0
	s_lshl_b32 s10, s10, 9
	global_load_dwordx4 v[54:57], v[42:43], off
	v_lshl_add_u64 v[44:45], s[38:39], 0, v[106:107]
	s_add_u32 s38, s33, s10
	global_load_dwordx4 v[50:53], v[42:43], off offset:1024
	s_addc_u32 s39, s36, 0
	global_load_dwordx4 v[46:49], v[42:43], off offset:2048
	s_or_b32 s10, s28, 16
	v_lshl_add_u64 v[66:67], v[44:45], 0, s[0:1]
	global_load_dwordx4 v[42:45], v[42:43], off offset:3072
	s_lshl_b32 s37, s10, 16
	v_lshl_add_u64 v[68:69], v[66:67], 0, s[8:9]
	global_load_dwordx2 v[134:135], v[66:67], off
	v_mov_b64_e32 v[66:67], s[38:39]
	s_add_u32 s38, s62, s37
	global_load_dwordx2 v[116:117], v[68:69], off
	s_addc_u32 s39, s63, 0
	s_lshl_b32 s37, s10, 15
	global_load_dword v132, v[66:67], off
	v_lshl_add_u64 v[66:67], s[38:39], 0, v[108:109]
	s_add_u32 s38, s64, s37
	v_lshl_add_u64 v[66:67], v[66:67], 0, s[6:7]
	s_addc_u32 s39, s65, 0
	s_lshl_b32 s10, s10, 9
	global_load_dwordx4 v[78:81], v[66:67], off
	v_lshl_add_u64 v[68:69], s[38:39], 0, v[106:107]
	s_add_u32 s38, s33, s10
	global_load_dwordx4 v[74:77], v[66:67], off offset:1024
	s_addc_u32 s39, s36, 0
	global_load_dwordx4 v[70:73], v[66:67], off offset:2048
	s_or_b32 s10, s28, 20
	v_lshl_add_u64 v[82:83], v[68:69], 0, s[0:1]
	global_load_dwordx4 v[66:69], v[66:67], off offset:3072
	s_lshl_b32 s37, s10, 16
	v_lshl_add_u64 v[84:85], v[82:83], 0, s[8:9]
	global_load_dwordx2 v[114:115], v[82:83], off
	v_mov_b64_e32 v[82:83], s[38:39]
	s_add_u32 s38, s62, s37
	global_load_dwordx2 v[110:111], v[84:85], off
	s_addc_u32 s39, s63, 0
	global_load_dword v112, v[82:83], off
	v_lshl_add_u64 v[82:83], s[38:39], 0, v[108:109]
	s_lshl_b32 s37, s10, 15
	v_lshl_add_u64 v[82:83], v[82:83], 0, s[6:7]
	s_add_u32 s38, s64, s37
	global_load_dwordx4 v[94:97], v[82:83], off
	s_addc_u32 s39, s65, 0
	global_load_dwordx4 v[90:93], v[82:83], off offset:1024
	v_lshl_add_u64 v[84:85], s[38:39], 0, v[106:107]
	s_lshl_b32 s10, s10, 9
	global_load_dwordx4 v[86:89], v[82:83], off offset:2048
	v_lshl_add_u64 v[100:101], v[84:85], 0, s[0:1]
	s_add_u32 s38, s33, s10
	global_load_dwordx4 v[82:85], v[82:83], off offset:3072
	v_lshl_add_u64 v[102:103], v[100:101], 0, s[8:9]
	s_addc_u32 s39, s36, 0
	global_load_dwordx2 v[104:105], v[100:101], off
	v_lshlrev_b32_e32 v145, 4, v234
	global_load_dwordx2 v[100:101], v[102:103], off
	v_mov_b64_e32 v[102:103], s[38:39]
	v_add_u32_e32 v1, 0, v145
	s_lshl_b32 s37, s48, 10
	global_load_dword v102, v[102:103], off
	v_add_u32_e32 v103, s0, v1
	s_and_b32 s10, s37, 0xfffff800
	v_add_u32_e32 v129, s10, v103
	s_mov_b32 s38, s1
	s_mov_b32 s39, s1
	s_or_b32 s10, s37, 0x400
	v_mov_b64_e32 v[120:121], s[38:39]
	v_add_u32_e32 v119, s10, v103
	ds_write_b64 v129, v[120:121]
	ds_write_b64 v119, v[120:121]
	s_waitcnt lgkmcnt(0)
	s_barrier
	ds_read_b128 v[120:123], v1 offset:7168
	ds_read_b128 v[146:149], v1 offset:6144
	ds_read_b128 v[150:153], v1 offset:5120
	ds_read_b128 v[154:157], v1 offset:4096
	ds_read_b128 v[158:161], v1 offset:3072
	ds_read_b128 v[162:165], v1 offset:2048
	ds_read_b128 v[166:169], v1 offset:1024
	ds_read_b128 v[170:173], v1
	s_waitcnt vmcnt(35)
	s_add_i32 s10, s37, 0
	v_mul_f32_e32 v118, 0, v113
	v_lshlrev_b32_e32 v174, 16, v124
	v_and_b32_e32 v175, 0xffff0000, v124
	v_lshlrev_b32_e32 v124, 16, v125
	v_and_b32_e32 v125, 0xffff0000, v125
	v_pk_add_f32 v[176:177], v[118:119], v[124:125] op_sel_hi:[0,1]
	v_pk_add_f32 v[174:175], v[118:119], v[174:175] op_sel_hi:[0,1]
	v_lshlrev_b32_e32 v124, 16, v142
	v_and_b32_e32 v125, 0xffff0000, v142
	v_lshlrev_b32_e32 v142, 16, v143
	v_and_b32_e32 v143, 0xffff0000, v143
	s_waitcnt lgkmcnt(0)
	v_mfma_f32_16x16x32_bf16 v[170:173], v[18:21], v[170:173], v[174:177]
	s_lshl_b32 s35, s35, 8
	s_or_b32 s42, s28, 24
	s_or_b32 s11, s35, s11
	v_pk_add_f32 v[176:177], v[118:119], v[142:143] op_sel_hi:[0,1]
	v_pk_add_f32 v[174:175], v[118:119], v[124:125] op_sel_hi:[0,1]
	v_mfma_f32_16x16x32_bf16 v[162:165], v[22:25], v[162:165], v[170:173]
	s_or_b32 s38, s29, 8
	s_or_b32 s39, s29, 9
	s_or_b32 s40, s29, 10
	v_mfma_f32_16x16x32_bf16 v[18:21], v[18:21], v[166:169], v[174:177]
	s_lshl_b32 s35, s29, 17
	s_or_b32 s41, s29, 11
	s_lshl_b32 s28, s42, 16
	v_mfma_f32_16x16x32_bf16 v[18:21], v[22:25], v[158:161], v[18:21]
	v_lshl_add_u64 v[22:23], s[64:65], 0, v[106:107]
	v_lshl_add_u64 v[124:125], v[22:23], 0, s[0:1]
	v_or_b32_e32 v106, s0, v106
	v_mfma_f32_16x16x32_bf16 v[22:25], v[10:13], v[154:157], v[162:165]
	v_add_u32_e32 v155, s10, v145
	s_or_b32 s10, s18, -4
	s_add_u32 s28, s62, s28
	v_mfma_f32_16x16x32_bf16 v[10:13], v[10:13], v[150:153], v[18:21]
	s_addc_u32 s29, s63, 0
	v_mfma_f32_16x16x32_bf16 v[146:149], v[2:5], v[146:149], v[22:25]
	v_mfma_f32_16x16x32_bf16 v[150:153], v[2:5], v[120:123], v[10:13]
	s_nop 0
	s_nop 0
	v_lshl_add_u64 v[2:3], s[28:29], 0, v[108:109]
	v_lshl_add_u64 v[2:3], v[2:3], 0, s[6:7]
	global_load_dwordx4 v[22:25], v[2:3], off
	s_lshl_b32 s28, s42, 15
	s_mov_b32 s29, s1
	global_load_dwordx4 v[18:21], v[2:3], off offset:1024
	v_lshl_add_u64 v[120:121], v[124:125], 0, s[28:29]
	s_lshl_b32 s28, s42, 9
	global_load_dwordx4 v[10:13], v[2:3], off offset:2048
	s_add_u32 s28, s33, s28
	global_load_dwordx4 v[2:5], v[2:3], off offset:3072
	v_lshl_add_u64 v[142:143], v[120:121], 0, s[8:9]
	s_addc_u32 s29, s36, 0
	global_load_dwordx2 v[122:123], v[120:121], off
	global_load_dwordx2 v[120:121], v[142:143], off
	v_mov_b64_e32 v[142:143], s[28:29]
	global_load_dword v118, v[142:143], off
	v_cvt_pk_bf16_f32 v142, v146, v147
	v_cvt_pk_bf16_f32 v143, v148, v149
	ds_write_b64 v129, v[142:143] offset:8192
	v_cvt_pk_bf16_f32 v142, v150, v151
	v_cvt_pk_bf16_f32 v143, v152, v153
	ds_write_b64 v119, v[142:143] offset:8192
	s_waitcnt lgkmcnt(0)
	s_barrier
	ds_read_b128 v[156:159], v1 offset:8192
	ds_read_b128 v[160:163], v1 offset:9216
	ds_read_b128 v[164:167], v1 offset:10240
	ds_read_b128 v[168:171], v1 offset:11264
	ds_read_b128 v[172:175], v1 offset:12288
	ds_read_b128 v[176:179], v1 offset:13312
	ds_read_b128 v[180:183], v1 offset:14336
	ds_read_b128 v[184:187], v1 offset:15360
	ds_read_b128 v[188:191], v155
	s_waitcnt vmcnt(35)
	s_add_i32 s28, s10, s19
	v_lshlrev_b32_e32 v192, 16, v140
	v_and_b32_e32 v193, 0xffff0000, v140
	v_lshlrev_b32_e32 v140, 16, v141
	v_and_b32_e32 v141, 0xffff0000, v141
	v_pk_fma_f32 v[142:143], v[148:149], v[138:139], v[140:141] op_sel_hi:[1,0,1]
	v_pk_fma_f32 v[140:141], v[146:147], v[138:139], v[192:193] op_sel_hi:[1,0,1]
	v_lshlrev_b32_e32 v146, 16, v136
	v_and_b32_e32 v147, 0xffff0000, v136
	v_lshlrev_b32_e32 v136, 16, v137
	v_and_b32_e32 v137, 0xffff0000, v137
	v_pk_fma_f32 v[148:149], v[152:153], v[138:139], v[136:137] op_sel_hi:[1,0,1]
	v_pk_fma_f32 v[146:147], v[150:151], v[138:139], v[146:147] op_sel_hi:[1,0,1]
	s_waitcnt lgkmcnt(8)
	v_mfma_f32_16x16x32_bf16 v[140:143], v[62:65], v[156:159], v[140:143]
	s_lshl_b32 s28, s28, 15
	s_add_i32 s28, s28, 0x20000
	s_mov_b32 s29, s1
	s_waitcnt lgkmcnt(7)
	v_mfma_f32_16x16x32_bf16 v[62:65], v[62:65], v[160:163], v[146:149]
	s_or_b32 s18, s19, s18
	s_waitcnt lgkmcnt(6)
	v_mfma_f32_16x16x32_bf16 v[136:139], v[58:61], v[164:167], v[140:143]
	s_waitcnt lgkmcnt(5)
	v_mfma_f32_16x16x32_bf16 v[58:61], v[58:61], v[168:171], v[62:65]
	s_waitcnt lgkmcnt(4)
	v_mfma_f32_16x16x32_bf16 v[62:65], v[14:17], v[172:175], v[136:139]
	s_waitcnt lgkmcnt(3)
	v_mfma_f32_16x16x32_bf16 v[14:17], v[14:17], v[176:179], v[58:61]
	s_nop 3
	v_or_b32_e32 v58, s3, v234
	v_add_u32_e32 v58, s11, v58
	v_ashrrev_i32_e32 v59, 31, v58
	v_lshl_add_u64 v[148:149], v[58:59], 4, s[64:65]
	s_waitcnt lgkmcnt(2)
	v_mfma_f32_16x16x32_bf16 v[156:159], v[6:9], v[180:183], v[62:65]
	s_waitcnt lgkmcnt(1)
	v_mfma_f32_16x16x32_bf16 v[160:163], v[6:9], v[184:187], v[14:17]
	v_lshl_add_u64 v[6:7], v[148:149], 0, s[28:29]
	s_or_b32 s28, s18, 28
	s_lshl_b32 s18, s28, 16
	s_add_u32 s18, s62, s18
	s_addc_u32 s19, s63, 0
	s_waitcnt lgkmcnt(0)
	global_store_dwordx4 v[6:7], v[188:191], off
	v_lshl_add_u64 v[6:7], s[18:19], 0, v[108:109]
	v_lshl_add_u64 v[6:7], v[6:7], 0, s[6:7]
	global_load_dwordx4 v[62:65], v[6:7], off
	s_lshl_b32 s18, s28, 15
	s_mov_b32 s19, s1
	global_load_dwordx4 v[58:61], v[6:7], off offset:1024
	v_lshl_add_u64 v[136:137], v[124:125], 0, s[18:19]
	s_lshl_b32 s18, s28, 9
	global_load_dwordx4 v[14:17], v[6:7], off offset:2048
	s_add_u32 s18, s33, s18
	global_load_dwordx4 v[6:9], v[6:7], off offset:3072
	s_addc_u32 s19, s36, 0
	global_load_dwordx2 v[150:151], v[136:137], off
	v_lshl_add_u64 v[138:139], v[136:137], 0, s[8:9]
	global_load_dwordx2 v[140:141], v[138:139], off
	v_mov_b64_e32 v[136:137], s[18:19]
	global_load_dword v138, v[136:137], off
	v_cvt_pk_bf16_f32 v136, v156, v157
	v_cvt_pk_bf16_f32 v137, v158, v159
	ds_write_b64 v129, v[136:137] offset:16384
	v_cvt_pk_bf16_f32 v136, v160, v161
	v_cvt_pk_bf16_f32 v137, v162, v163
	ds_write_b64 v119, v[136:137] offset:16384
	s_waitcnt lgkmcnt(0)
	s_barrier
	ds_read_b128 v[164:167], v1 offset:16384
	ds_read_b128 v[168:171], v1 offset:17408
	ds_read_b128 v[172:175], v1 offset:18432
	ds_read_b128 v[176:179], v1 offset:19456
	ds_read_b128 v[180:183], v1 offset:20480
	ds_read_b128 v[184:187], v1 offset:21504
	ds_read_b128 v[188:191], v1 offset:22528
	ds_read_b128 v[192:195], v1 offset:23552
	ds_read_b128 v[196:199], v155 offset:8192
	s_waitcnt vmcnt(35)
	s_lshl_b32 s18, s10, 15
	v_lshlrev_b32_e32 v136, 16, v130
	v_and_b32_e32 v137, 0xffff0000, v130
	v_lshlrev_b32_e32 v130, 16, v131
	v_and_b32_e32 v131, 0xffff0000, v131
	v_pk_fma_f32 v[158:159], v[158:159], v[128:129], v[130:131] op_sel_hi:[1,0,1]
	v_lshlrev_b32_e32 v130, 16, v126
	v_and_b32_e32 v131, 0xffff0000, v126
	v_lshlrev_b32_e32 v126, 16, v127
	v_and_b32_e32 v127, 0xffff0000, v127
	v_pk_fma_f32 v[156:157], v[156:157], v[128:129], v[136:137] op_sel_hi:[1,0,1]
	v_pk_fma_f32 v[162:163], v[162:163], v[128:129], v[126:127] op_sel_hi:[1,0,1]
	v_pk_fma_f32 v[160:161], v[160:161], v[128:129], v[130:131] op_sel_hi:[1,0,1]
	s_waitcnt lgkmcnt(8)
	v_mfma_f32_16x16x32_bf16 v[156:159], v[38:41], v[164:167], v[156:159]
	s_add_i32 s18, s18, s35
	s_lshl_b32 s19, s38, 2
	s_add_i32 s28, s18, 0x40000
	s_waitcnt lgkmcnt(7)
	v_mfma_f32_16x16x32_bf16 v[38:41], v[38:41], v[168:171], v[160:163]
	s_or_b32 s19, s19, s5
	s_waitcnt lgkmcnt(6)
	v_mfma_f32_16x16x32_bf16 v[156:159], v[34:37], v[172:175], v[156:159]
	s_waitcnt lgkmcnt(5)
	v_mfma_f32_16x16x32_bf16 v[34:37], v[34:37], v[176:179], v[38:41]
	s_waitcnt lgkmcnt(4)
	v_mfma_f32_16x16x32_bf16 v[38:41], v[30:33], v[180:183], v[156:159]
	s_waitcnt lgkmcnt(3)
	v_mfma_f32_16x16x32_bf16 v[30:33], v[30:33], v[184:187], v[34:37]
	s_waitcnt lgkmcnt(2)
	v_mfma_f32_16x16x32_bf16 v[156:159], v[26:29], v[188:191], v[38:41]
	s_waitcnt lgkmcnt(1)
	v_mfma_f32_16x16x32_bf16 v[160:163], v[26:29], v[192:195], v[30:33]
	v_lshl_add_u64 v[26:27], v[148:149], 0, s[28:29]
	s_lshl_b32 s28, s19, 16
	s_add_u32 s28, s62, s28
	s_addc_u32 s29, s63, 0
	s_waitcnt lgkmcnt(0)
	global_store_dwordx4 v[26:27], v[196:199], off
	v_lshl_add_u64 v[26:27], s[28:29], 0, v[108:109]
	v_lshl_add_u64 v[26:27], v[26:27], 0, s[6:7]
	global_load_dwordx4 v[38:41], v[26:27], off
	global_load_dwordx4 v[34:37], v[26:27], off offset:1024
	s_lshl_b32 s28, s19, 15
	s_mov_b32 s29, s1
	s_lshl_b32 s19, s19, 9
	global_load_dwordx4 v[30:33], v[26:27], off offset:2048
	v_lshl_add_u64 v[126:127], v[124:125], 0, s[28:29]
	s_add_u32 s28, s33, s19
	global_load_dwordx4 v[26:29], v[26:27], off offset:3072
	v_lshl_add_u64 v[136:137], v[126:127], 0, s[8:9]
	s_addc_u32 s29, s36, 0
	global_load_dwordx2 v[130:131], v[126:127], off
	global_load_dwordx2 v[126:127], v[136:137], off
	v_mov_b64_e32 v[136:137], s[28:29]
	global_load_dword v128, v[136:137], off
	v_cvt_pk_bf16_f32 v136, v156, v157
	v_cvt_pk_bf16_f32 v137, v158, v159
	ds_write_b64 v129, v[136:137]
	v_cvt_pk_bf16_f32 v136, v160, v161
	v_cvt_pk_bf16_f32 v137, v162, v163
	ds_write_b64 v119, v[136:137]
	s_waitcnt lgkmcnt(0)
	s_barrier
	ds_read_b128 v[164:167], v1
	ds_read_b128 v[168:171], v1 offset:1024
	ds_read_b128 v[172:175], v1 offset:2048
	ds_read_b128 v[176:179], v1 offset:3072
	ds_read_b128 v[180:183], v1 offset:4096
	ds_read_b128 v[184:187], v1 offset:5120
	ds_read_b128 v[188:191], v1 offset:6144
	ds_read_b128 v[192:195], v1 offset:7168
	ds_read_b128 v[196:199], v155 offset:16384
	s_waitcnt vmcnt(35)
	s_lshl_b32 s19, s39, 2
	v_lshlrev_b32_e32 v142, 16, v134
	v_and_b32_e32 v143, 0xffff0000, v134
	v_lshlrev_b32_e32 v134, 16, v135
	v_and_b32_e32 v135, 0xffff0000, v135
	v_pk_fma_f32 v[136:137], v[158:159], v[132:133], v[134:135] op_sel_hi:[1,0,1]
	v_pk_fma_f32 v[134:135], v[156:157], v[132:133], v[142:143] op_sel_hi:[1,0,1]
	v_lshlrev_b32_e32 v142, 16, v116
	v_and_b32_e32 v143, 0xffff0000, v116
	v_lshlrev_b32_e32 v116, 16, v117
	v_and_b32_e32 v117, 0xffff0000, v117
	v_pk_fma_f32 v[158:159], v[162:163], v[132:133], v[116:117] op_sel_hi:[1,0,1]
	v_pk_fma_f32 v[156:157], v[160:161], v[132:133], v[142:143] op_sel_hi:[1,0,1]
	s_waitcnt lgkmcnt(8)
	v_mfma_f32_16x16x32_bf16 v[134:137], v[54:57], v[164:167], v[134:137]
	s_add_i32 s28, s18, 0x60000
	s_mov_b32 s29, s1
	s_or_b32 s19, s19, s5
	s_waitcnt lgkmcnt(7)
	v_mfma_f32_16x16x32_bf16 v[54:57], v[54:57], v[168:171], v[156:159]
	s_waitcnt lgkmcnt(6)
	v_mfma_f32_16x16x32_bf16 v[132:135], v[50:53], v[172:175], v[134:137]
	s_waitcnt lgkmcnt(5)
	v_mfma_f32_16x16x32_bf16 v[50:53], v[50:53], v[176:179], v[54:57]
	s_waitcnt lgkmcnt(4)
	v_mfma_f32_16x16x32_bf16 v[54:57], v[46:49], v[180:183], v[132:135]
	s_waitcnt lgkmcnt(3)
	v_mfma_f32_16x16x32_bf16 v[46:49], v[46:49], v[184:187], v[50:53]
	s_waitcnt lgkmcnt(2)
	v_mfma_f32_16x16x32_bf16 v[156:159], v[42:45], v[188:191], v[54:57]
	s_waitcnt lgkmcnt(1)
	v_mfma_f32_16x16x32_bf16 v[160:163], v[42:45], v[192:195], v[46:49]
	v_lshl_add_u64 v[42:43], v[148:149], 0, s[28:29]
	s_lshl_b32 s28, s19, 16
	s_add_u32 s28, s62, s28
	s_addc_u32 s29, s63, 0
	s_waitcnt lgkmcnt(0)
	global_store_dwordx4 v[42:43], v[196:199], off
	v_lshl_add_u64 v[42:43], s[28:29], 0, v[108:109]
	v_lshl_add_u64 v[42:43], v[42:43], 0, s[6:7]
	global_load_dwordx4 v[54:57], v[42:43], off
	global_load_dwordx4 v[50:53], v[42:43], off offset:1024
	s_lshl_b32 s28, s19, 15
	s_mov_b32 s29, s1
	s_lshl_b32 s19, s19, 9
	global_load_dwordx4 v[46:49], v[42:43], off offset:2048
	v_lshl_add_u64 v[116:117], v[124:125], 0, s[28:29]
	s_add_u32 s28, s33, s19
	global_load_dwordx4 v[42:45], v[42:43], off offset:3072
	v_lshl_add_u64 v[132:133], v[116:117], 0, s[8:9]
	s_addc_u32 s29, s36, 0
	global_load_dwordx2 v[136:137], v[116:117], off
	global_load_dwordx2 v[132:133], v[132:133], off
	v_mov_b64_e32 v[116:117], s[28:29]
	global_load_dword v134, v[116:117], off
	v_cvt_pk_bf16_f32 v116, v156, v157
	v_cvt_pk_bf16_f32 v117, v158, v159
	ds_write_b64 v129, v[116:117] offset:8192
	v_cvt_pk_bf16_f32 v116, v160, v161
	v_cvt_pk_bf16_f32 v117, v162, v163
	ds_write_b64 v119, v[116:117] offset:8192
	s_waitcnt lgkmcnt(0)
	s_barrier
	ds_read_b128 v[164:167], v1 offset:8192
	ds_read_b128 v[168:171], v1 offset:9216
	ds_read_b128 v[172:175], v1 offset:10240
	ds_read_b128 v[176:179], v1 offset:11264
	ds_read_b128 v[180:183], v1 offset:12288
	ds_read_b128 v[184:187], v1 offset:13312
	ds_read_b128 v[188:191], v1 offset:14336
	ds_read_b128 v[192:195], v1 offset:15360
	ds_read_b128 v[196:199], v155
	s_waitcnt vmcnt(35)
	s_lshl_b32 s19, s40, 2
	v_lshlrev_b32_e32 v142, 16, v114
	v_and_b32_e32 v143, 0xffff0000, v114
	v_lshlrev_b32_e32 v114, 16, v115
	v_and_b32_e32 v115, 0xffff0000, v115
	v_pk_fma_f32 v[116:117], v[158:159], v[112:113], v[114:115] op_sel_hi:[1,0,1]
	v_pk_fma_f32 v[114:115], v[156:157], v[112:113], v[142:143] op_sel_hi:[1,0,1]
	v_lshlrev_b32_e32 v142, 16, v110
	v_and_b32_e32 v143, 0xffff0000, v110
	v_lshlrev_b32_e32 v110, 16, v111
	v_and_b32_e32 v111, 0xffff0000, v111
	v_pk_fma_f32 v[158:159], v[162:163], v[112:113], v[110:111] op_sel_hi:[1,0,1]
	v_pk_fma_f32 v[156:157], v[160:161], v[112:113], v[142:143] op_sel_hi:[1,0,1]
	s_waitcnt lgkmcnt(8)
	v_mfma_f32_16x16x32_bf16 v[114:117], v[78:81], v[164:167], v[114:117]
	s_add_i32 s28, s18, 0x80000
	s_mov_b32 s29, s1
	s_or_b32 s19, s19, s5
	s_waitcnt lgkmcnt(7)
	v_mfma_f32_16x16x32_bf16 v[78:81], v[78:81], v[168:171], v[156:159]
	s_waitcnt lgkmcnt(6)
	v_mfma_f32_16x16x32_bf16 v[110:113], v[74:77], v[172:175], v[114:117]
	s_waitcnt lgkmcnt(5)
	v_mfma_f32_16x16x32_bf16 v[74:77], v[74:77], v[176:179], v[78:81]
	s_waitcnt lgkmcnt(4)
	v_mfma_f32_16x16x32_bf16 v[78:81], v[70:73], v[180:183], v[110:113]
	s_waitcnt lgkmcnt(3)
	v_mfma_f32_16x16x32_bf16 v[70:73], v[70:73], v[184:187], v[74:77]
	s_waitcnt lgkmcnt(2)
	v_mfma_f32_16x16x32_bf16 v[110:113], v[66:69], v[188:191], v[78:81]
	s_waitcnt lgkmcnt(1)
	v_mfma_f32_16x16x32_bf16 v[114:117], v[66:69], v[192:195], v[70:73]
	v_lshl_add_u64 v[66:67], v[148:149], 0, s[28:29]
	s_lshl_b32 s28, s19, 16
	s_add_u32 s28, s62, s28
	s_addc_u32 s29, s63, 0
	s_waitcnt lgkmcnt(0)
	global_store_dwordx4 v[66:67], v[196:199], off
	v_lshl_add_u64 v[66:67], s[28:29], 0, v[108:109]
	v_lshl_add_u64 v[66:67], v[66:67], 0, s[6:7]
	global_load_dwordx4 v[78:81], v[66:67], off
	global_load_dwordx4 v[74:77], v[66:67], off offset:1024
	s_lshl_b32 s28, s19, 15
	s_mov_b32 s29, s1
	s_lshl_b32 s19, s19, 9
	global_load_dwordx4 v[70:73], v[66:67], off offset:2048
	v_lshl_add_u64 v[142:143], v[124:125], 0, s[28:29]
	s_add_u32 s28, s33, s19
	global_load_dwordx4 v[66:69], v[66:67], off offset:3072
	v_lshl_add_u64 v[152:153], v[142:143], 0, s[8:9]
	s_addc_u32 s29, s36, 0
	global_load_dwordx2 v[146:147], v[142:143], off
	global_load_dwordx2 v[142:143], v[152:153], off
	v_mov_b64_e32 v[152:153], s[28:29]
	global_load_dword v144, v[152:153], off
	v_cvt_pk_bf16_f32 v152, v110, v111
	v_cvt_pk_bf16_f32 v153, v112, v113
	ds_write_b64 v129, v[152:153] offset:16384
	v_cvt_pk_bf16_f32 v152, v114, v115
	v_cvt_pk_bf16_f32 v153, v116, v117
	ds_write_b64 v119, v[152:153] offset:16384
	s_waitcnt lgkmcnt(0)
	s_barrier
;     const int b = job >> 4, h = (job >> 2) & 3, sl = job & 3;
;     f32x4 acc[2]; acc[0] = (f32x4){0.f, 0.f, 0.f, 0.f}; acc[1] = acc[0];
;     DnPre p0, p1, p2, p3, p4, p5;
;     DN_ISSUE(p0, 0); DN_ISSUE(p1, 1); DN_ISSUE(p2, 2); DN_ISSUE(p3, 3); DN_ISSUE(p4, 4); DN_ISSUE(p5, 5);
;     for (int n0 = 0; n0 < 126; n0 += 6) {
;         DN_STEP(p0, n0, 0, true, MODE); DN_STEP(p1, n0 + 1, 1, true, MODE); DN_STEP(p2, n0 + 2, 2, true, MODE); DN_STEP(p3, n0 + 3, 0, true, MODE); DN_STEP(p4, n0 + 4, 1, true, MODE); DN_STEP(p5, n0 + 5, 2, true, MODE);
	ds_read_b128 v[156:159], v1 offset:16384
	ds_read_b128 v[160:163], v1 offset:17408
	ds_read_b128 v[164:167], v1 offset:18432
	ds_read_b128 v[168:171], v1 offset:19456
	ds_read_b128 v[172:175], v1 offset:20480
	ds_read_b128 v[176:179], v1 offset:21504
	ds_read_b128 v[180:183], v1 offset:22528
	ds_read_b128 v[184:187], v1 offset:23552
	ds_read_b128 v[188:191], v155 offset:8192
	s_waitcnt vmcnt(35)
	s_add_i32 s18, s18, 0xa0000
	v_lshlrev_b32_e32 v152, 16, v104
	v_and_b32_e32 v153, 0xffff0000, v104
	v_lshlrev_b32_e32 v104, 16, v105
	v_and_b32_e32 v105, 0xffff0000, v105
	v_pk_fma_f32 v[110:111], v[110:111], v[102:103], v[152:153] op_sel_hi:[1,0,1]
	v_lshlrev_b32_e32 v152, 16, v100
	v_and_b32_e32 v153, 0xffff0000, v100
	v_lshlrev_b32_e32 v100, 16, v101
	v_and_b32_e32 v101, 0xffff0000, v101
	v_pk_fma_f32 v[112:113], v[112:113], v[102:103], v[104:105] op_sel_hi:[1,0,1]
	v_pk_fma_f32 v[104:105], v[116:117], v[102:103], v[100:101] op_sel_hi:[1,0,1]
	v_pk_fma_f32 v[102:103], v[114:115], v[102:103], v[152:153] op_sel_hi:[1,0,1]
	s_waitcnt lgkmcnt(8)
	v_mfma_f32_16x16x32_bf16 v[110:113], v[94:97], v[156:159], v[110:113]
	s_mov_b32 s19, s1
	s_waitcnt lgkmcnt(7)
	v_mfma_f32_16x16x32_bf16 v[94:97], v[94:97], v[160:163], v[102:105]
	s_waitcnt lgkmcnt(6)
	v_mfma_f32_16x16x32_bf16 v[100:103], v[90:93], v[164:167], v[110:113]
	s_waitcnt lgkmcnt(5)
	v_mfma_f32_16x16x32_bf16 v[90:93], v[90:93], v[168:171], v[94:97]
	s_nop 0
	v_lshlrev_b64 v[110:111], 3, v[98:99]
	s_waitcnt lgkmcnt(4)
	v_mfma_f32_16x16x32_bf16 v[94:97], v[86:89], v[172:175], v[100:103]
	v_lshlrev_b64 v[174:175], 1, v[110:111]
	s_waitcnt lgkmcnt(3)
	v_mfma_f32_16x16x32_bf16 v[86:89], v[86:89], v[176:179], v[90:93]
	s_waitcnt lgkmcnt(2)
	v_mfma_f32_16x16x32_bf16 v[102:105], v[82:85], v[180:183], v[94:97]
	s_waitcnt lgkmcnt(1)
	v_mfma_f32_16x16x32_bf16 v[98:101], v[82:85], v[184:187], v[86:89]
	v_lshl_add_u64 v[82:83], v[148:149], 0, s[18:19]
	s_lshl_b32 s18, s41, 2
	s_or_b32 s28, s18, s5
	s_lshl_b32 s18, s28, 16
	s_add_u32 s18, s62, s18
	s_addc_u32 s19, s63, 0
	s_waitcnt lgkmcnt(0)
	global_store_dwordx4 v[82:83], v[188:191], off
	v_lshl_add_u64 v[82:83], s[18:19], 0, v[108:109]
	s_lshl_b32 s18, s28, 15
	s_mov_b32 s19, s1
	v_lshl_add_u64 v[82:83], v[82:83], 0, s[6:7]
	v_lshl_add_u64 v[108:109], v[124:125], 0, s[18:19]
	s_lshl_b32 s18, s28, 9
	global_load_dwordx4 v[94:97], v[82:83], off
	s_add_u32 s18, s33, s18
	global_load_dwordx4 v[90:93], v[82:83], off offset:1024
	s_addc_u32 s19, s36, 0
	global_load_dwordx4 v[86:89], v[82:83], off offset:2048
	s_add_i32 s11, s11, s3
	s_lshl_b32 s3, s2, 7
	global_load_dwordx4 v[82:85], v[82:83], off offset:3072
	s_and_b32 s3, s3, 0x200
	global_load_dwordx2 v[156:157], v[108:109], off
	v_or_b32_e32 v148, s11, v234
	s_add_i32 s10, s10, s3
	v_lshl_add_u64 v[112:113], v[108:109], 0, s[8:9]
	global_load_dwordx2 v[152:153], v[112:113], off
	v_mov_b64_e32 v[108:109], s[18:19]
	v_ashrrev_i32_e32 v149, 31, v148
	s_lshl_b32 s45, s10, 15
	global_load_dword v154, v[108:109], off
	v_lshlrev_b64 v[108:109], 4, v[148:149]
	s_add_i32 s10, s45, 0xe0000
	s_mov_b32 s11, s1
	v_lshl_add_u64 v[112:113], v[108:109], 0, s[10:11]
	s_mov_b64 s[28:29], 0xc00000
	s_add_i32 s10, s45, 0x160000
	v_lshl_add_u64 v[158:159], v[112:113], 0, s[28:29]
	v_lshl_add_u64 v[112:113], v[108:109], 0, s[10:11]
	s_add_i32 s10, s45, 0x140000
	v_lshl_add_u64 v[160:161], v[112:113], 0, s[28:29]
	v_lshl_add_u64 v[112:113], v[108:109], 0, s[10:11]
	s_add_i32 s10, s45, 0x120000
	v_lshl_add_u64 v[162:163], v[112:113], 0, s[28:29]
	v_lshl_add_u64 v[112:113], v[108:109], 0, s[10:11]
	s_add_i32 s10, s45, 0x100000
	s_or_b32 s3, s3, s5
	v_lshl_add_u64 v[164:165], v[112:113], 0, s[28:29]
	v_lshl_add_u64 v[112:113], v[108:109], 0, s[10:11]
	s_or_b32 s10, s3, 52
	s_lshl_b32 s11, s10, 16
	s_add_u32 s35, s11, 0xa004000
	s_addc_u32 s42, 0, 0
	s_lshl_b32 s0, s10, 15
	v_lshl_add_u64 v[166:167], v[112:113], 0, s[28:29]
	v_lshl_add_u64 v[112:113], v[106:107], 0, s[0:1]
	s_lshl_b32 s0, s10, 9
	s_add_u32 s10, s33, s0
	s_addc_u32 s11, s36, 0
	s_or_b32 s3, s3, 48
	s_lshl_b32 s0, s3, 16
	s_add_u32 s43, s0, 0xa004000
	s_addc_u32 s44, 0, 0
	s_lshl_b32 s0, s3, 15
	v_lshl_add_u64 v[106:107], v[106:107], 0, s[0:1]
	s_lshl_b32 s0, s3, 9
	s_add_u32 s18, s33, s0
	s_addc_u32 s19, s36, 0
	s_add_i32 s0, s45, 0xc0000
	v_lshl_add_u64 v[170:171], v[106:107], 0, s[28:29]
	v_lshl_add_u64 v[106:107], v[108:109], 0, s[0:1]
	v_lshl_add_u64 v[168:169], v[112:113], 0, s[28:29]
	v_lshl_add_u64 v[172:173], v[106:107], 0, s[28:29]
	s_mov_b64 s[28:29], 0xc0000
	s_mov_b32 s45, 0

; #define LAS __attribute__((address_space(3)))
; __global__ void __launch_bounds__(NWAVES * 64, 2) fwd(Args args) {
;     extern __shared__ __attribute__((aligned(16))) unsigned char lds_raw[];
;     LAS unsigned char* lds = (LAS unsigned char*)lds_raw;
;     volatile LAS unsigned* MISC = (volatile LAS unsigned*)(lds + MISC_OFF);
;     const int tid = threadIdx.x, lane = tid & 63, wave = __builtin_amdgcn_readfirstlane(tid >> 6);
	.amdhsa_kernel _Z3fwd4Args
		.amdhsa_group_segment_fixed_size 0
		.amdhsa_private_segment_fixed_size 0
		.amdhsa_kernarg_size 424
		.amdhsa_user_sgpr_count 2
		.amdhsa_user_sgpr_dispatch_ptr 0
		.amdhsa_user_sgpr_queue_ptr 0
		.amdhsa_user_sgpr_kernarg_segment_ptr 1
		.amdhsa_user_sgpr_dispatch_id 0
		.amdhsa_user_sgpr_kernarg_preload_length 0
		.amdhsa_user_sgpr_kernarg_preload_offset 0
		.amdhsa_user_sgpr_private_segment_size 0
		.amdhsa_uses_dynamic_stack 0
		.amdhsa_enable_private_segment 0
		.amdhsa_system_sgpr_workgroup_id_x 1
		.amdhsa_system_sgpr_workgroup_id_y 0
		.amdhsa_system_sgpr_workgroup_id_z 0
		.amdhsa_system_sgpr_workgroup_info 0
		.amdhsa_system_vgpr_workitem_id 0
		.amdhsa_next_free_vgpr 248
		.amdhsa_next_free_sgpr 98
		.amdhsa_accum_offset 244
		.amdhsa_reserve_vcc 1
		.amdhsa_float_round_mode_32 0
		.amdhsa_float_round_mode_16_64 0
		.amdhsa_float_denorm_mode_32 3
		.amdhsa_float_denorm_mode_16_64 3
		.amdhsa_dx10_clamp 1
		.amdhsa_ieee_mode 1
		.amdhsa_fp16_overflow 0
		.amdhsa_tg_split 0
		.amdhsa_exception_fp_ieee_invalid_op 0
		.amdhsa_exception_fp_denorm_src 0
		.amdhsa_exception_fp_ieee_div_zero 0
		.amdhsa_exception_fp_ieee_overflow 0
		.amdhsa_exception_fp_ieee_underflow 0
		.amdhsa_exception_fp_ieee_inexact 0
		.amdhsa_exception_int_div_zero 0
	.end_amdhsa_kernel

; #define LAS __attribute__((address_space(3)))
; __global__ void __launch_bounds__(NWAVES * 64, 2) fwd(Args args) {
;     extern __shared__ __attribute__((aligned(16))) unsigned char lds_raw[];
;     LAS unsigned char* lds = (LAS unsigned char*)lds_raw;
;     volatile LAS unsigned* MISC = (volatile LAS unsigned*)(lds + MISC_OFF);
;     const int tid = threadIdx.x, lane = tid & 63, wave = __builtin_amdgcn_readfirstlane(tid >> 6);
amdhsa.kernels:
  - .agpr_count:     0
    .args:
      - .offset:         0
        .size:           168
        .value_kind:     by_value
      - .offset:         168
        .size:           4
        .value_kind:     hidden_block_count_x
      - .offset:         172
        .size:           4
        .value_kind:     hidden_block_count_y
      - .offset:         176
        .size:           4
        .value_kind:     hidden_block_count_z
      - .offset:         180
        .size:           2
        .value_kind:     hidden_group_size_x
      - .offset:         182
        .size:           2
        .value_kind:     hidden_group_size_y
      - .offset:         184
        .size:           2
        .value_kind:     hidden_group_size_z
      - .offset:         186
        .size:           2
        .value_kind:     hidden_remainder_x
      - .offset:         188
        .size:           2
        .value_kind:     hidden_remainder_y
      - .offset:         190
        .size:           2
        .value_kind:     hidden_remainder_z
      - .offset:         208
        .size:           8
        .value_kind:     hidden_global_offset_x
      - .offset:         216
        .size:           8
        .value_kind:     hidden_global_offset_y
      - .offset:         224
        .size:           8
        .value_kind:     hidden_global_offset_z
      - .offset:         232
        .size:           2
        .value_kind:     hidden_grid_dims
      - .offset:         288
        .size:           4
        .value_kind:     hidden_dynamic_lds_size
    .group_segment_fixed_size: 0
    .kernarg_segment_align: 8
    .kernarg_segment_size: 424
    .language:       OpenCL C
    .language_version:
      - 2
      - 0
    .max_flat_workgroup_size: 512
    .name:           _Z3fwd4Args
    .private_segment_fixed_size: 0
    .sgpr_count:     104
    .sgpr_spill_count: 37
    .symbol:         _Z3fwd4Args.kd
    .uniform_work_group_size: 1
    .uses_dynamic_stack: false
    .vgpr_count:     248
    .vgpr_spill_count: 0
    .wavefront_size: 64
